# v33: v30 + S5 item start: the U-tile and KT loads are issued before the LDS-reuse barrier instead of after it (barrier skew overlaps the load latency)
# baseline (speedup 1.0000x reference)
; DEV int opaque_tid() { int t = threadIdx.x; asm volatile("" : "+v"(t)); return t; }
; #define LAS __attribute__((address_space(3)))
; DEV void s5_phase(LAS char* shm, const bf16_t* Uin, bf16_t* Yout, const char* tab, const float* dskip) {
;     ...
;     for (int item = blockIdx.x; item < BATCH * NG; item += gridDim.x) {
;         const int tid = opaque_tid(), wid = __builtin_amdgcn_readfirstlane(tid >> 6), lane = tid & 63, fr = lane & 15, fq = lane >> 4;
;         const int xcd_ = item & 7, j_ = (item >> 3) & 31, g = xcd_ * 8 + (j_ & 7), b = (j_ >> 3) + 4 * (item >> 8);
;         const bf16_t* Ub = Uin + ((size_t)g * MTOK + (size_t)b * SEQ) * 16;
;         bf16_t* Yb = Yout + ((size_t)g * MTOK + (size_t)b * SEQ) * 16;
;         bf16x8 wfr[8];
;         const bf16_t* wsp = WS + (size_t)g * WS_G + ((size_t)(wid * 16) * 64 + lane) * 8; asm volatile("" : "+v"(wsp));
; #pragma unroll
;         for (int sp = 0; sp < 8; ++sp) wfr[sp] = *(const bf16x8*)(wsp + (size_t)sp * 64 * 8);
;         __syncthreads();
; #pragma unroll
;         for (int i = 0; i < 8; ++i) {
;             const int idx = tid + 512 * i, tok = idx >> 1, hf = idx & 1;
;             const uint4 uv = *(const uint4*)(Ub + (size_t)tok * 16 + hf * 8);
;             *(LAS u32x4*)(shm + hf * PLANE + (tok >> 5) * 528 + (tok & 31) * 16) = (u32x4){uv.x, uv.y, uv.z, uv.w};
;         }
;         for (int idx = tid; idx < 33 * 32; idx += 512) {
;             const uint4 kv = *(const uint4*)(KT + (size_t)g * KT_G + idx * 8);
;             *(LAS u32x4*)(shm + KTL + idx * 16) = (u32x4){kv.x, kv.y, kv.z, kv.w};
;         }
;         __syncthreads();
.LBB0_288:
	s_lshl_b32 s0, s44, 3
	s_and_b32 s0, s0, 56
	s_bfe_u32 s1, s44, 0x30003
	s_or_b32 s47, s0, s1
	s_ashr_i32 s1, s44, 6
	s_bfe_u32 s0, s44, 0x20006
	s_and_b32 s1, s1, -4
	v_mov_b32_e32 v172, v254
	s_or_b32 s0, s0, s1
	s_ashr_i32 s1, s0, 31
	v_readfirstlane_b32 s46, v172
	s_ashr_i32 s45, s46, 6
	s_lshl_b64 s[0:1], s[0:1], 15
	s_lshl_b32 s6, s47, 18
	s_add_u32 s0, s6, s0
	s_addc_u32 s1, 0, s1
	s_lshl_b64 s[8:9], s[0:1], 1
	s_add_u32 s0, s17, s8
	s_addc_u32 s1, s18, s9
	s_lshl_b32 s6, s47, 17
	s_add_u32 s12, s23, s6
	s_addc_u32 s13, s24, 0
	s_lshl_b32 s6, s45, 4
	s_ashr_i32 s7, s6, 31
	s_lshl_b64 s[10:11], s[6:7], 10
	v_and_b32_e32 v173, 63, v172
	s_add_u32 s10, s12, s10
	s_addc_u32 s11, s13, s11
	v_lshlrev_b32_e32 v166, 4, v173
	v_lshl_add_u64 v[168:169], s[10:11], 0, v[166:167]
	v_and_b32_e32 v0, 1, v172
	v_add_co_u32_e32 v2, vcc, s27, v168
	v_ashrrev_i32_e32 v66, 1, v172
	s_nop 0
	v_addc_co_u32_e32 v3, vcc, 0, v169, vcc
	global_load_dwordx4 v[46:49], v[168:169], off
	global_load_dwordx4 v[42:45], v[168:169], off offset:1024
	global_load_dwordx4 v[38:41], v[168:169], off offset:2048
	global_load_dwordx4 v[34:37], v[168:169], off offset:3072
	global_load_dwordx4 v[30:33], v[2:3], off
	global_load_dwordx4 v[26:29], v[2:3], off offset:1024
	global_load_dwordx4 v[22:25], v[2:3], off offset:2048
	global_load_dwordx4 v[18:21], v[2:3], off offset:3072
	v_lshlrev_b32_e32 v2, 4, v0
	v_mov_b32_e32 v3, v167
	v_ashrrev_i32_e32 v67, 31, v66
	v_lshl_add_u64 v[62:63], s[0:1], 0, v[2:3]
	v_lshlrev_b64 v[2:3], 5, v[66:67]
	v_add_u32_e32 v1, 0x200, v172
	v_lshl_add_u64 v[2:3], v[62:63], 0, v[2:3]
	v_ashrrev_i32_e32 v68, 1, v1
	global_load_dwordx4 v[2:5], v[2:3], off
	v_ashrrev_i32_e32 v69, 31, v68
	v_lshlrev_b64 v[6:7], 5, v[68:69]
	v_add_u32_e32 v67, 0x400, v172
	v_lshl_add_u64 v[6:7], v[62:63], 0, v[6:7]
	v_ashrrev_i32_e32 v70, 1, v67
	global_load_dwordx4 v[6:9], v[6:7], off
	v_ashrrev_i32_e32 v71, 31, v70
	v_lshlrev_b64 v[10:11], 5, v[70:71]
	v_add_u32_e32 v69, 0x600, v172
	v_lshl_add_u64 v[10:11], v[62:63], 0, v[10:11]
	v_ashrrev_i32_e32 v72, 1, v69
	global_load_dwordx4 v[10:13], v[10:11], off
	v_ashrrev_i32_e32 v73, 31, v72
	v_lshlrev_b64 v[14:15], 5, v[72:73]
	v_add_u32_e32 v71, 0x800, v172
	v_lshl_add_u64 v[14:15], v[62:63], 0, v[14:15]
	v_ashrrev_i32_e32 v74, 1, v71
	global_load_dwordx4 v[14:17], v[14:15], off
	v_ashrrev_i32_e32 v75, 31, v74
	v_lshlrev_b64 v[50:51], 5, v[74:75]
	v_add_u32_e32 v73, 0xa00, v172
	v_lshl_add_u64 v[50:51], v[62:63], 0, v[50:51]
	v_ashrrev_i32_e32 v76, 1, v73
	global_load_dwordx4 v[50:53], v[50:51], off
	v_ashrrev_i32_e32 v77, 31, v76
	v_lshlrev_b64 v[54:55], 5, v[76:77]
	v_add_u32_e32 v75, 0xc00, v172
	v_lshl_add_u64 v[54:55], v[62:63], 0, v[54:55]
	v_ashrrev_i32_e32 v78, 1, v75
	global_load_dwordx4 v[54:57], v[54:55], off
	v_ashrrev_i32_e32 v79, 31, v78
	v_lshlrev_b64 v[58:59], 5, v[78:79]
	v_add_u32_e32 v77, 0xe00, v172
	v_lshl_add_u64 v[58:59], v[62:63], 0, v[58:59]
	v_ashrrev_i32_e32 v80, 1, v77
	global_load_dwordx4 v[58:61], v[58:59], off
	v_ashrrev_i32_e32 v81, 31, v80
	v_lshlrev_b64 v[64:65], 5, v[80:81]
	v_lshl_add_u64 v[62:63], v[62:63], 0, v[64:65]
	global_load_dwordx4 v[62:65], v[62:63], off
	v_ashrrev_i32_e32 v79, 6, v172
	v_lshlrev_b32_e32 v66, 4, v66
	v_mad_u32_u24 v0, v0, s28, 0
	v_mul_lo_u32 v79, v79, s29
	v_and_b32_e32 v66, 0x1f0, v66
	v_add3_u32 v66, v0, v79, v66
	v_ashrrev_i32_e32 v1, 6, v1
	v_mul_lo_u32 v1, v1, s29
	v_cmp_gt_i32_e32 vcc, s30, v172
	s_mul_i32 s56, s47, 0x4200
	s_add_u32 s54, s21, s56
	s_addc_u32 s55, s22, 0
	v_lshlrev_b32_e32 v192, 3, v172
	v_mov_b32_e32 v193, 0
	v_lshl_add_u64 v[194:195], v[192:193], 1, s[54:55]
	global_load_dwordx4 v[180:183], v[194:195], off
	s_mov_b64 s[56:57], 0x2000
	v_lshl_add_u64 v[196:197], v[194:195], 0, s[56:57]
	global_load_dwordx4 v[184:187], v[196:197], off
	v_cmp_gt_i32_e64 s[60:61], 32, v172
	v_lshl_add_u64 v[196:197], v[196:197], 0, s[56:57]
	s_and_saveexec_b64 s[56:57], s[60:61]
	global_load_dwordx4 v[188:191], v[196:197], off
	s_or_b64 exec, exec, s[56:57]
	s_waitcnt lgkmcnt(0)
	s_barrier
	s_waitcnt vmcnt(0)
	ds_write_b128 v66, v[2:5]
	v_lshlrev_b32_e32 v2, 4, v68
	v_and_b32_e32 v2, 0x1f0, v2
	v_add3_u32 v1, v0, v1, v2
	v_lshlrev_b32_e32 v2, 4, v70
	v_and_b32_e32 v2, 0x1f0, v2
	ds_write_b128 v1, v[6:9]
	v_ashrrev_i32_e32 v1, 6, v67
	v_mul_lo_u32 v1, v1, s29
	v_add3_u32 v1, v0, v1, v2
	v_lshlrev_b32_e32 v2, 4, v72
	v_and_b32_e32 v2, 0x1f0, v2
	ds_write_b128 v1, v[10:13]
	v_ashrrev_i32_e32 v1, 6, v69
	v_mul_lo_u32 v1, v1, s29
	v_add3_u32 v1, v0, v1, v2
	v_lshlrev_b32_e32 v2, 4, v74
	v_and_b32_e32 v2, 0x1f0, v2
	ds_write_b128 v1, v[14:17]
	v_ashrrev_i32_e32 v1, 6, v71
	v_mul_lo_u32 v1, v1, s29
	v_add3_u32 v1, v0, v1, v2
	v_lshlrev_b32_e32 v2, 4, v76
	v_and_b32_e32 v2, 0x1f0, v2
	ds_write_b128 v1, v[50:53]
	v_ashrrev_i32_e32 v1, 6, v73
	v_mul_lo_u32 v1, v1, s29
	v_add3_u32 v1, v0, v1, v2
	v_lshlrev_b32_e32 v2, 4, v78
	v_and_b32_e32 v2, 0x1f0, v2
	ds_write_b128 v1, v[54:57]
	v_ashrrev_i32_e32 v1, 6, v75
	v_mul_lo_u32 v1, v1, s29
	v_add3_u32 v1, v0, v1, v2
	v_lshlrev_b32_e32 v2, 4, v80
	v_and_b32_e32 v2, 0x1f0, v2
	ds_write_b128 v1, v[58:61]
	v_ashrrev_i32_e32 v1, 6, v77
	v_mul_lo_u32 v1, v1, s29
	v_add3_u32 v0, v0, v1, v2
	ds_write_b128 v0, v[62:65]
	s_and_saveexec_b64 s[0:1], vcc
	s_cbranch_execz .LBB0_291
	s_mul_i32 s7, s47, 0x4200
	s_add_u32 s10, s21, s7
	s_addc_u32 s11, s22, 0
	v_add_u32_e32 v4, 0xfffffe00, v172
	v_lshl_add_u32 v5, v172, 4, s31
	v_lshlrev_b32_e32 v2, 3, v172
	s_mov_b64 s[12:13], 0

; DEV int opaque_tid() { int t = threadIdx.x; asm volatile("" : "+v"(t)); return t; }
; #define LAS __attribute__((address_space(3)))
; DEV void s5_phase(LAS char* shm, const bf16_t* Uin, bf16_t* Yout, const char* tab, const float* dskip) {
;     ...
;     for (int item = blockIdx.x; item < BATCH * NG; item += gridDim.x) {
;         const int tid = opaque_tid(), wid = __builtin_amdgcn_readfirstlane(tid >> 6), lane = tid & 63, fr = lane & 15, fq = lane >> 4;
;         const int xcd_ = item & 7, j_ = (item >> 3) & 31, g = xcd_ * 8 + (j_ & 7), b = (j_ >> 3) + 4 * (item >> 8);
;         const bf16_t* Ub = Uin + ((size_t)g * MTOK + (size_t)b * SEQ) * 16;
;         bf16_t* Yb = Yout + ((size_t)g * MTOK + (size_t)b * SEQ) * 16;
;         bf16x8 wfr[8];
;         const bf16_t* wsp = WS + (size_t)g * WS_G + ((size_t)(wid * 16) * 64 + lane) * 8; asm volatile("" : "+v"(wsp));
; #pragma unroll
;         for (int sp = 0; sp < 8; ++sp) wfr[sp] = *(const bf16x8*)(wsp + (size_t)sp * 64 * 8);
;         __syncthreads();
; #pragma unroll
;         for (int i = 0; i < 8; ++i) {
;             const int idx = tid + 512 * i, tok = idx >> 1, hf = idx & 1;
;             const uint4 uv = *(const uint4*)(Ub + (size_t)tok * 16 + hf * 8);
;             *(LAS u32x4*)(shm + hf * PLANE + (tok >> 5) * 528 + (tok & 31) * 16) = (u32x4){uv.x, uv.y, uv.z, uv.w};
;         }
;         for (int idx = tid; idx < 33 * 32; idx += 512) {
;             const uint4 kv = *(const uint4*)(KT + (size_t)g * KT_G + idx * 8);
;             *(LAS u32x4*)(shm + KTL + idx * 16) = (u32x4){kv.x, kv.y, kv.z, kv.w};
;         }
;         __syncthreads();
.LBB0_1143:
	s_lshl_b32 s0, s42, 3
	s_and_b32 s0, s0, 56
	s_bfe_u32 s1, s42, 0x30003
	s_or_b32 s45, s0, s1
	s_ashr_i32 s1, s42, 6
	s_bfe_u32 s0, s42, 0x20006
	s_and_b32 s1, s1, -4
	v_mov_b32_e32 v172, v254
	s_or_b32 s0, s0, s1
	s_ashr_i32 s1, s0, 31
	v_readfirstlane_b32 s44, v172
	s_ashr_i32 s43, s44, 6
	s_lshl_b64 s[0:1], s[0:1], 15
	s_lshl_b32 s6, s45, 18
	s_add_u32 s0, s6, s0
	s_addc_u32 s1, 0, s1
	s_lshl_b64 s[8:9], s[0:1], 1
	s_add_u32 s0, s15, s8
	s_addc_u32 s1, s16, s9
	s_lshl_b32 s6, s45, 17
	s_add_u32 s12, s23, s6
	s_addc_u32 s13, s24, 0
	s_lshl_b32 s6, s43, 4
	s_ashr_i32 s7, s6, 31
	s_lshl_b64 s[10:11], s[6:7], 10
	v_and_b32_e32 v173, 63, v172
	s_add_u32 s10, s12, s10
	s_addc_u32 s11, s13, s11
	v_lshlrev_b32_e32 v166, 4, v173
	v_lshl_add_u64 v[168:169], s[10:11], 0, v[166:167]
	v_and_b32_e32 v82, 1, v172
	v_add_co_u32_e32 v0, vcc, s27, v168
	v_ashrrev_i32_e32 v66, 1, v172
	s_nop 0
	v_addc_co_u32_e32 v1, vcc, 0, v169, vcc
	global_load_dwordx4 v[46:49], v[168:169], off
	global_load_dwordx4 v[42:45], v[168:169], off offset:1024
	global_load_dwordx4 v[38:41], v[168:169], off offset:2048
	global_load_dwordx4 v[34:37], v[168:169], off offset:3072
	global_load_dwordx4 v[30:33], v[0:1], off
	global_load_dwordx4 v[26:29], v[0:1], off offset:1024
	global_load_dwordx4 v[22:25], v[0:1], off offset:2048
	global_load_dwordx4 v[18:21], v[0:1], off offset:3072
	v_lshlrev_b32_e32 v0, 4, v82
	v_mov_b32_e32 v1, v167
	v_ashrrev_i32_e32 v67, 31, v66
	v_lshl_add_u64 v[0:1], s[0:1], 0, v[0:1]
	v_lshlrev_b64 v[2:3], 5, v[66:67]
	v_add_u32_e32 v67, 0x200, v172
	v_lshl_add_u64 v[2:3], v[0:1], 0, v[2:3]
	v_ashrrev_i32_e32 v68, 1, v67
	global_load_dwordx4 v[2:5], v[2:3], off
	v_ashrrev_i32_e32 v69, 31, v68
	v_lshlrev_b64 v[6:7], 5, v[68:69]
	v_add_u32_e32 v69, 0x400, v172
	v_lshl_add_u64 v[6:7], v[0:1], 0, v[6:7]
	v_ashrrev_i32_e32 v70, 1, v69
	global_load_dwordx4 v[6:9], v[6:7], off
	v_ashrrev_i32_e32 v71, 31, v70
	v_lshlrev_b64 v[10:11], 5, v[70:71]
	v_add_u32_e32 v71, 0x600, v172
	v_lshl_add_u64 v[10:11], v[0:1], 0, v[10:11]
	v_ashrrev_i32_e32 v72, 1, v71
	global_load_dwordx4 v[10:13], v[10:11], off
	v_ashrrev_i32_e32 v73, 31, v72
	v_lshlrev_b64 v[14:15], 5, v[72:73]
	v_add_u32_e32 v73, 0x800, v172
	v_lshl_add_u64 v[14:15], v[0:1], 0, v[14:15]
	v_ashrrev_i32_e32 v74, 1, v73
	global_load_dwordx4 v[14:17], v[14:15], off
	v_ashrrev_i32_e32 v75, 31, v74
	v_lshlrev_b64 v[50:51], 5, v[74:75]
	v_add_u32_e32 v75, 0xa00, v172
	v_lshl_add_u64 v[50:51], v[0:1], 0, v[50:51]
	v_ashrrev_i32_e32 v76, 1, v75
	global_load_dwordx4 v[50:53], v[50:51], off
	v_ashrrev_i32_e32 v77, 31, v76
	v_lshlrev_b64 v[54:55], 5, v[76:77]
	v_add_u32_e32 v77, 0xc00, v172
	v_lshl_add_u64 v[54:55], v[0:1], 0, v[54:55]
	v_ashrrev_i32_e32 v78, 1, v77
	global_load_dwordx4 v[54:57], v[54:55], off
	v_ashrrev_i32_e32 v79, 31, v78
	v_lshlrev_b64 v[58:59], 5, v[78:79]
	v_add_u32_e32 v79, 0xe00, v172
	v_lshl_add_u64 v[58:59], v[0:1], 0, v[58:59]
	v_ashrrev_i32_e32 v80, 1, v79
	global_load_dwordx4 v[58:61], v[58:59], off
	v_ashrrev_i32_e32 v81, 31, v80
	v_lshlrev_b64 v[62:63], 5, v[80:81]
	v_lshl_add_u64 v[0:1], v[0:1], 0, v[62:63]
	global_load_dwordx4 v[62:65], v[0:1], off
	v_ashrrev_i32_e32 v1, 6, v172
	v_lshlrev_b32_e32 v66, 4, v66
	v_mad_u32_u24 v0, v82, s28, 0
	v_mul_lo_u32 v1, v1, s29
	v_and_b32_e32 v66, 0x1f0, v66
	v_add3_u32 v1, v0, v1, v66
	v_cmp_gt_i32_e32 vcc, s30, v172
	s_mul_i32 s56, s45, 0x4200
	s_add_u32 s54, s19, s56
	s_addc_u32 s55, s20, 0
	v_lshlrev_b32_e32 v192, 3, v172
	v_mov_b32_e32 v193, 0
	v_lshl_add_u64 v[194:195], v[192:193], 1, s[54:55]
	global_load_dwordx4 v[180:183], v[194:195], off
	s_mov_b64 s[56:57], 0x2000
	v_lshl_add_u64 v[196:197], v[194:195], 0, s[56:57]
	global_load_dwordx4 v[184:187], v[196:197], off
	v_cmp_gt_i32_e64 s[60:61], 32, v172
	v_lshl_add_u64 v[196:197], v[196:197], 0, s[56:57]
	s_and_saveexec_b64 s[56:57], s[60:61]
	global_load_dwordx4 v[188:191], v[196:197], off
	s_or_b64 exec, exec, s[56:57]
	s_waitcnt lgkmcnt(0)
	s_barrier
	s_waitcnt vmcnt(0)
	ds_write_b128 v1, v[2:5]
	v_ashrrev_i32_e32 v1, 6, v67
	v_lshlrev_b32_e32 v2, 4, v68
	v_mul_lo_u32 v1, v1, s29
	v_and_b32_e32 v2, 0x1f0, v2
	v_add3_u32 v1, v0, v1, v2
	ds_write_b128 v1, v[6:9]
	v_ashrrev_i32_e32 v1, 6, v69
	v_lshlrev_b32_e32 v2, 4, v70
	v_mul_lo_u32 v1, v1, s29
	v_and_b32_e32 v2, 0x1f0, v2
	v_add3_u32 v1, v0, v1, v2
	ds_write_b128 v1, v[10:13]
	v_ashrrev_i32_e32 v1, 6, v71
	v_lshlrev_b32_e32 v2, 4, v72
	v_mul_lo_u32 v1, v1, s29
	v_and_b32_e32 v2, 0x1f0, v2
	v_add3_u32 v1, v0, v1, v2
	ds_write_b128 v1, v[14:17]
	v_ashrrev_i32_e32 v1, 6, v73
	v_lshlrev_b32_e32 v2, 4, v74
	v_mul_lo_u32 v1, v1, s29
	v_and_b32_e32 v2, 0x1f0, v2
	v_add3_u32 v1, v0, v1, v2
	ds_write_b128 v1, v[50:53]
	v_ashrrev_i32_e32 v1, 6, v75
	v_lshlrev_b32_e32 v2, 4, v76
	v_mul_lo_u32 v1, v1, s29
	v_and_b32_e32 v2, 0x1f0, v2
	v_add3_u32 v1, v0, v1, v2
	ds_write_b128 v1, v[54:57]
	v_ashrrev_i32_e32 v1, 6, v77
	v_lshlrev_b32_e32 v2, 4, v78
	v_mul_lo_u32 v1, v1, s29
	v_and_b32_e32 v2, 0x1f0, v2
	v_add3_u32 v1, v0, v1, v2
	ds_write_b128 v1, v[58:61]
	v_ashrrev_i32_e32 v1, 6, v79
	v_lshlrev_b32_e32 v2, 4, v80
	v_mul_lo_u32 v1, v1, s29
	v_and_b32_e32 v2, 0x1f0, v2
	v_add3_u32 v0, v0, v1, v2
	ds_write_b128 v0, v[62:65]
	s_and_saveexec_b64 s[0:1], vcc
	s_cbranch_execz .LBB0_1146
	s_mul_i32 s7, s45, 0x4200
	s_add_u32 s10, s19, s7
	s_addc_u32 s11, s20, 0
	v_add_u32_e32 v4, 0xfffffe00, v172
	v_lshl_add_u32 v5, v172, 4, s31
	v_lshlrev_b32_e32 v2, 3, v172
	s_mov_b64 s[12:13], 0
